# conv data loads issued at the start of SWA's last head (after its final vmcnt(0)) into free registers; at the conv site they are register copies behind a counted wait
# baseline (speedup 1.0000x reference)
; #define GAS __attribute__((address_space(1)))
; __device__ __forceinline__ void swa_item(LAS unsigned char* lds, const GAS bf16_t* proj, GAS bf16_t* mix, const GAS float* sinks, int nb, int hk, int tid, int w, int lane) {
;     ...
;         const float sink = sinks[hq];
;         float mx = sink;
; #pragma unroll
;         for (int j = 0; j < 9; ++j)
; #pragma unroll
;             for (int i = 0; i < 4; ++i) { const int kpos = 16 * (w + j) + 4 * fq + i;
;                 if (j == 0) s[j][i] = kpos > ql ? s[j][i] : -1e30f;
;                 if (j == 8) s[j][i] = kpos <= ql + 128 ? s[j][i] : -1e30f; }
;         if (nb == 0) {
; #pragma unroll
;             for (int j = 0; j < 9; ++j)
; #pragma unroll
;                 for (int i = 0; i < 4; ++i) s[j][i] = (16 * (w + j) + 4 * fq + i) >= 128 ? s[j][i] : -1e30f;
;         }
; #pragma unroll
;         for (int j = 0; j < 9; ++j)
; #pragma unroll
;             for (int i = 0; i < 4; ++i) mx = fmaxf(mx, s[j][i]);
;         mx = fmaxf(mx, __shfl_xor(mx, 16)); mx = fmaxf(mx, __shfl_xor(mx, 32));
;         float sum = 0.f; const float nmx = -mx * 1.4426950408889634f;
; #pragma unroll
;         for (int j = 0; j < 9; ++j)
; #pragma unroll
;             for (int i = 0; i < 4; ++i) { const float p = __builtin_amdgcn_exp2f(__builtin_fmaf(s[j][i], 1.4426950408889634f, nmx)); s[j][i] = p; sum += p; }
;         sum += __shfl_xor(sum, 16); sum += __shfl_xor(sum, 32);
;         const float inv = __builtin_amdgcn_rcpf(sum + __expf(sink - mx));
; __device__ __forceinline__ void conv_phase(const GAS bf16_t* proj, const GAS float* cw, const GAS float* cb_, GAS bf16_t* mix, int tid, int G, int bid) {
;     for (int it0 = bid * 512 + tid; it0 < (SEQ / 4) * 32; it0 += G * 512) {
;         const int it = (G == 256) ? (((512 * (bid & 7) + 16 * (bid >> 3)) << 5) + tid) : it0;
;         const int t0 = (it >> 5) * 4, c8 = (it & 31) * 8;
;         u32x4 ccr[6], cur[6], cbr[4];
; #pragma unroll
;         for (int r = 0; r < 6; ++r) { const int tt = t0 - 2 + r;
;             ccr[r] = (u32x4){0u, 0u, 0u, 0u}; cur[r] = (u32x4){0u, 0u, 0u, 0u};
;             if (tt >= 0) { ccr[r] = *(const GAS u32x4*)(proj + PJ(tt, C_CC + c8)); cur[r] = *(const GAS u32x4*)(proj + PJ(tt, C_CU + c8)); } }
; #pragma unroll
;         for (int q = 0; q < 4; ++q) cbr[q] = *(const GAS u32x4*)(proj + PJ(t0 + q, C_CB + c8));
.LBB0_411:
	s_waitcnt vmcnt(0)
	v_readlane_b32 s98, v254, 47
	v_and_b32_e32 v242, 31, v0
	v_lshrrev_b32_e32 v246, 5, v0
	s_and_b32 s99, s98, 7
	s_lshr_b32 s98, s98, 3
	s_lshl_b32 s99, s99, 9
	s_lshl_b32 s98, s98, 4
	s_add_i32 s98, s98, s99
	v_add_u32_e32 v246, s98, v246
	v_lshlrev_b32_e32 v246, 2, v246
	v_lshlrev_b32_e32 v242, 3, v242
	v_lshrrev_b32_e32 v243, 6, v242
	v_and_b32_e32 v242, 63, v242
	v_lshlrev_b32_e32 v243, 21, v243
	v_lshl_add_u32 v242, v242, 1, v243
	v_lshl_add_u32 v242, v246, 7, v242
	v_add_u32_e32 v243, 0x4c00000, v242
	v_add_u32_e32 v244, 0x5400000, v242
	v_add_u32_e32 v245, 0x4400000, v242
	v_mov_b32_e32 v154, 0
	v_mov_b32_e32 v155, 0
	v_mov_b32_e32 v156, 0
	v_mov_b32_e32 v157, 0
	v_mov_b32_e32 v158, 0
	v_mov_b32_e32 v159, 0
	v_mov_b32_e32 v160, 0
	v_mov_b32_e32 v161, 0
	v_mov_b32_e32 v180, 0
	v_mov_b32_e32 v181, 0
	v_mov_b32_e32 v182, 0
	v_mov_b32_e32 v183, 0
	v_mov_b32_e32 v186, 0
	v_mov_b32_e32 v187, 0
	v_mov_b32_e32 v188, 0
	v_mov_b32_e32 v189, 0
	v_cmp_lt_u32_e64 s[100:101], 3, v246
	s_and_saveexec_b64 s[98:99], s[100:101]
	global_load_dwordx4 v[154:157], v243, s[94:95] offset:-256
	global_load_dwordx4 v[180:183], v244, s[94:95] offset:-256
	global_load_dwordx4 v[158:161], v243, s[94:95] offset:-128
	global_load_dwordx4 v[186:189], v244, s[94:95] offset:-128
	s_mov_b64 exec, s[98:99]
	global_load_dwordx4 v[162:165], v243, s[94:95]
	global_load_dwordx4 v[190:193], v244, s[94:95]
	global_load_dwordx4 v[166:169], v243, s[94:95] offset:128
	global_load_dwordx4 v[196:199], v244, s[94:95] offset:128
	global_load_dwordx4 v[170:173], v243, s[94:95] offset:256
	global_load_dwordx4 v[200:203], v244, s[94:95] offset:256
	global_load_dwordx4 v[174:177], v243, s[94:95] offset:384
	global_load_dwordx4 v[204:207], v244, s[94:95] offset:384
	global_load_dwordx4 v[208:211], v245, s[94:95]
	global_load_dwordx4 v[212:215], v245, s[94:95] offset:128
	global_load_dwordx4 v[216:219], v245, s[94:95] offset:256
	global_load_dwordx4 v[228:231], v245, s[94:95] offset:384
	v_max3_f32 v5, v4, v41, v40
	v_max3_f32 v5, v5, v11, v10
	v_max3_f32 v5, v5, v36, v37
	v_max3_f32 v5, v5, v38, v39
	v_max3_f32 v5, v5, v32, v33
	v_max3_f32 v5, v5, v34, v35
	v_max3_f32 v5, v5, v28, v29
	v_max3_f32 v5, v5, v30, v31
	v_max3_f32 v5, v5, v24, v25
	v_max3_f32 v5, v5, v26, v27
	v_max3_f32 v5, v5, v20, v21
	v_max3_f32 v5, v5, v22, v23
	v_max3_f32 v5, v5, v12, v13
	v_max3_f32 v5, v5, v14, v15
	v_max3_f32 v5, v5, v16, v17
	v_max3_f32 v5, v5, v18, v19
	v_max3_f32 v5, v5, v9, v8
	v_max3_f32 v5, v5, v7, v6
	ds_bpermute_b32 v42, v75, v5
	s_lshl_b32 s0, s59, 8
	s_addk_i32 s0, 0x600
	v_readlane_b32 s60, v254, 55
	v_readlane_b32 s61, v254, 56
	s_waitcnt lgkmcnt(0)
	v_max_f32_e32 v42, v42, v42
	v_max_f32_e32 v5, v5, v42
	ds_bpermute_b32 v42, v76, v5
	s_mov_b64 s[62:63], s[64:65]
	s_waitcnt lgkmcnt(0)
	v_max_f32_e32 v42, v42, v42
	v_max_f32_e32 v5, v5, v42
	v_mul_f32_e32 v42, 0xbfb8aa3b, v5
	v_fmamk_f32 v41, v41, 0x3fb8aa3b, v42
	v_exp_f32_e32 v41, v41
	v_fmamk_f32 v40, v40, 0x3fb8aa3b, v42
	v_exp_f32_e32 v40, v40
	v_fmamk_f32 v11, v11, 0x3fb8aa3b, v42
	v_exp_f32_e32 v44, v11
	v_add_f32_e32 v43, 0, v41
	v_add_f32_e32 v43, v40, v43
	v_fmamk_f32 v10, v10, 0x3fb8aa3b, v42
	v_add_f32_e32 v11, v44, v43
	v_exp_f32_e32 v43, v10
	v_fmamk_f32 v9, v9, 0x3fb8aa3b, v42
	v_exp_f32_e32 v9, v9
	v_fmamk_f32 v8, v8, 0x3fb8aa3b, v42
	v_add_f32_e32 v10, v43, v11
	v_fmamk_f32 v11, v36, 0x3fb8aa3b, v42
	v_exp_f32_e32 v36, v11
	v_fmamk_f32 v11, v37, 0x3fb8aa3b, v42
	v_exp_f32_e32 v37, v11
	v_fmamk_f32 v11, v38, 0x3fb8aa3b, v42
	v_exp_f32_e32 v38, v11
	v_fmamk_f32 v11, v39, 0x3fb8aa3b, v42
	v_exp_f32_e32 v39, v11
	v_fmamk_f32 v11, v32, 0x3fb8aa3b, v42
	v_exp_f32_e32 v32, v11
	v_fmamk_f32 v11, v33, 0x3fb8aa3b, v42
	v_exp_f32_e32 v33, v11
	v_fmamk_f32 v11, v34, 0x3fb8aa3b, v42
	v_exp_f32_e32 v34, v11
	v_fmamk_f32 v11, v35, 0x3fb8aa3b, v42
	v_exp_f32_e32 v35, v11
	v_fmamk_f32 v11, v28, 0x3fb8aa3b, v42
	v_exp_f32_e32 v45, v11
	v_fmamk_f32 v11, v29, 0x3fb8aa3b, v42
	v_exp_f32_e32 v46, v11
	v_fmamk_f32 v11, v30, 0x3fb8aa3b, v42
	v_exp_f32_e32 v47, v11
	v_fmamk_f32 v11, v31, 0x3fb8aa3b, v42
	v_exp_f32_e32 v48, v11
	v_fmamk_f32 v11, v24, 0x3fb8aa3b, v42
	v_exp_f32_e32 v51, v11
	v_fmamk_f32 v11, v25, 0x3fb8aa3b, v42
	v_exp_f32_e32 v52, v11
	v_fmamk_f32 v11, v26, 0x3fb8aa3b, v42
	v_exp_f32_e32 v53, v11
	v_fmamk_f32 v11, v27, 0x3fb8aa3b, v42
	v_exp_f32_e32 v54, v11
	v_fmamk_f32 v11, v20, 0x3fb8aa3b, v42
	v_exp_f32_e32 v55, v11
	v_fmamk_f32 v11, v21, 0x3fb8aa3b, v42
	v_exp_f32_e32 v56, v11
	v_fmamk_f32 v11, v22, 0x3fb8aa3b, v42
	v_exp_f32_e32 v57, v11
	v_fmamk_f32 v11, v23, 0x3fb8aa3b, v42
	v_exp_f32_e32 v58, v11
	v_fmamk_f32 v11, v12, 0x3fb8aa3b, v42
	v_exp_f32_e32 v59, v11
	v_fmamk_f32 v11, v13, 0x3fb8aa3b, v42
	v_exp_f32_e32 v66, v11
	v_fmamk_f32 v11, v14, 0x3fb8aa3b, v42
	v_exp_f32_e32 v67, v11
	v_fmamk_f32 v11, v15, 0x3fb8aa3b, v42
	v_exp_f32_e32 v132, v11
	v_fmamk_f32 v11, v16, 0x3fb8aa3b, v42
	v_add_f32_e32 v10, v36, v10
	v_exp_f32_e32 v133, v11
	v_fmamk_f32 v11, v17, 0x3fb8aa3b, v42
	v_add_f32_e32 v10, v37, v10
	v_exp_f32_e32 v134, v11
	v_fmamk_f32 v11, v18, 0x3fb8aa3b, v42
	v_add_f32_e32 v10, v38, v10
	v_exp_f32_e32 v135, v11
	v_fmamk_f32 v11, v19, 0x3fb8aa3b, v42
	v_cvt_pk_bf16_f32 v12, v41, v40
	v_cvt_pk_bf16_f32 v13, v44, v43
	v_cvt_pk_bf16_f32 v14, v36, v37
	v_cvt_pk_bf16_f32 v15, v38, v39
	ds_read_b64 v[16:17], v77 offset:36864
	ds_read_b64 v[18:19], v78 offset:36864
	ds_read_b64 v[20:21], v79 offset:36864
	ds_read_b64 v[22:23], v80 offset:36864
	ds_read_b64 v[24:25], v81 offset:36864
	ds_read_b64 v[26:27], v82 offset:36864
	ds_read_b64 v[28:29], v83 offset:36864
	ds_read_b64 v[30:31], v84 offset:36864
	v_add_f32_e32 v10, v39, v10
	v_add_f32_e32 v10, v32, v10
	v_add_f32_e32 v10, v33, v10
	v_add_f32_e32 v10, v34, v10
	v_add_f32_e32 v10, v35, v10
	s_waitcnt lgkmcnt(6)
; __device__ __forceinline__ unsigned cvt_pk_bf16(float lo, float hi) { unsigned r; asm volatile("v_cvt_pk_bf16_f32 %0, %1, %2" : "=v"(r) : "v"(lo), "v"(hi)); return r; }
; #define LAS __attribute__((address_space(3)))
; #define GAS __attribute__((address_space(1)))
; __device__ __forceinline__ size_t TX(int row, int col) { return ((((size_t)(row >> 8) * 16 + (col >> 6)) * 256 + (row & 255)) << 6) + (col & 63); }
; __device__ __forceinline__ int tsw(int d) { return ((d >> 3) & 7) << 3; }
; #define MFMA16(a, b, c) __builtin_amdgcn_mfma_f32_16x16x32_bf16(a, b, c, 0, 0, 0)
; __device__ __forceinline__ void swa_item(LAS unsigned char* lds, const GAS bf16_t* proj, GAS bf16_t* mix, const GAS float* sinks, int nb, int hk, int tid, int w, int lane) {
;     ...
; #pragma unroll
;         for (int jj = 0; jj < 5; ++jj) {
;             const int j0 = 2 * jj, j1 = 2 * jj + 1;
;             u32x2 plo, phi; plo.x = cvt_pk_bf16(s[j0][0], s[j0][1]); plo.y = cvt_pk_bf16(s[j0][2], s[j0][3]);
;             if (j1 < 9) { phi.x = cvt_pk_bf16(s[j1 < 9 ? j1 : 0][0], s[j1 < 9 ? j1 : 0][1]); phi.y = cvt_pk_bf16(s[j1 < 9 ? j1 : 0][2], s[j1 < 9 ? j1 : 0][3]); } else { phi.x = 0u; phi.y = 0u; }
;             const bf16x8 pb = mk8(plo, phi);
; #pragma unroll
;             for (int et = 0; et < 4; ++et) {
;                 const LAS bf16_t* vr = VTs + (16 * et + fr) * VS; const int sw = tsw(16 * et + fr), kc0 = 16 * (w + j0) + 4 * fq;
;                 const u32x2 a0 = *(const LAS u32x2*)(vr + (kc0 ^ sw)), a1 = *(const LAS u32x2*)(vr + ((kc0 + 16) ^ sw));
;                 o[et] = MFMA16(mk8(a0, a1), pb, o[et]);
;             }
;         }
; #pragma unroll
;         for (int et = 0; et < 4; ++et) { const f32x4 v = o[et] * inv; u32x2 wv; wv.x = cvt_pk_bf16(v[0], v[1]); wv.y = cvt_pk_bf16(v[2], v[3]);
;             *(GAS u32x2*)(mix + TX(tq, MIX_SWA + 64 * hq + 16 * et + 4 * fq)) = wv; }
;     }
;     __syncthreads();
	v_mfma_f32_16x16x32_bf16 v[16:19], v[16:19], v[12:15], 0
	v_add_f32_e32 v10, v45, v10
	v_add_f32_e32 v10, v46, v10
	v_add_f32_e32 v10, v47, v10
	s_waitcnt lgkmcnt(4)
	v_mfma_f32_16x16x32_bf16 v[20:23], v[20:23], v[12:15], 0
	v_add_f32_e32 v10, v48, v10
	v_add_f32_e32 v10, v51, v10
	v_add_f32_e32 v10, v52, v10
	s_waitcnt lgkmcnt(2)
	v_mfma_f32_16x16x32_bf16 v[24:27], v[24:27], v[12:15], 0
	v_add_f32_e32 v10, v53, v10
	v_add_f32_e32 v10, v54, v10
	v_add_f32_e32 v10, v55, v10
	s_waitcnt lgkmcnt(0)
	v_mfma_f32_16x16x32_bf16 v[12:15], v[28:31], v[12:15], 0
	v_cvt_pk_bf16_f32 v28, v32, v33
	v_cvt_pk_bf16_f32 v29, v34, v35
	v_cvt_pk_bf16_f32 v30, v45, v46
	v_cvt_pk_bf16_f32 v31, v47, v48
	ds_read_b64 v[32:33], v85 offset:36864
	ds_read_b64 v[34:35], v86 offset:36864
	s_waitcnt lgkmcnt(0)
	v_mfma_f32_16x16x32_bf16 v[16:19], v[32:35], v[28:31], v[16:19]
	ds_read_b64 v[32:33], v87 offset:36864
	ds_read_b64 v[34:35], v88 offset:36864
	v_add_f32_e32 v10, v56, v10
	v_add_f32_e32 v10, v57, v10
	s_waitcnt lgkmcnt(0)
	v_mfma_f32_16x16x32_bf16 v[20:23], v[32:35], v[28:31], v[20:23]
	ds_read_b64 v[32:33], v89 offset:36864
	ds_read_b64 v[34:35], v90 offset:36864
	v_add_f32_e32 v10, v58, v10
	v_add_f32_e32 v10, v59, v10
	s_waitcnt lgkmcnt(0)
	v_mfma_f32_16x16x32_bf16 v[24:27], v[32:35], v[28:31], v[24:27]
	ds_read_b64 v[32:33], v91 offset:36864
	ds_read_b64 v[34:35], v92 offset:36864
	v_add_f32_e32 v10, v66, v10
	v_add_f32_e32 v10, v67, v10
	s_waitcnt lgkmcnt(0)
	v_mfma_f32_16x16x32_bf16 v[12:15], v[32:35], v[28:31], v[12:15]
	v_cvt_pk_bf16_f32 v28, v51, v52
	v_cvt_pk_bf16_f32 v29, v53, v54
	v_cvt_pk_bf16_f32 v30, v55, v56
	v_cvt_pk_bf16_f32 v31, v57, v58
	ds_read_b64 v[32:33], v93 offset:36864
	ds_read_b64 v[34:35], v94 offset:36864
	s_waitcnt lgkmcnt(0)
	v_mfma_f32_16x16x32_bf16 v[16:19], v[32:35], v[28:31], v[16:19]
	ds_read_b64 v[32:33], v95 offset:36864
	ds_read_b64 v[34:35], v96 offset:36864
	v_add_f32_e32 v10, v132, v10
	v_exp_f32_e32 v136, v11
	s_waitcnt lgkmcnt(0)
	v_mfma_f32_16x16x32_bf16 v[20:23], v[32:35], v[28:31], v[20:23]
	ds_read_b64 v[32:33], v97 offset:36864
	ds_read_b64 v[34:35], v98 offset:36864
	v_add_f32_e32 v10, v133, v10
	v_add_f32_e32 v10, v134, v10
	s_waitcnt lgkmcnt(0)
	v_mfma_f32_16x16x32_bf16 v[24:27], v[32:35], v[28:31], v[24:27]
	ds_read_b64 v[32:33], v99 offset:36864
	ds_read_b64 v[34:35], v100 offset:36864
	v_exp_f32_e32 v8, v8
	v_add_f32_e32 v10, v135, v10
	s_waitcnt lgkmcnt(0)
	v_mfma_f32_16x16x32_bf16 v[12:15], v[32:35], v[28:31], v[12:15]
	v_cvt_pk_bf16_f32 v28, v59, v66
	v_cvt_pk_bf16_f32 v29, v67, v132
	v_cvt_pk_bf16_f32 v30, v133, v134
	v_cvt_pk_bf16_f32 v31, v135, v136
	ds_read_b64 v[32:33], v101 offset:36864
	ds_read_b64 v[34:35], v102 offset:36864
	v_add_f32_e32 v10, v136, v10
	v_add_f32_e32 v10, v9, v10
	v_fmamk_f32 v7, v7, 0x3fb8aa3b, v42
	v_add_f32_e32 v11, v8, v10
	v_exp_f32_e32 v10, v7
	s_waitcnt lgkmcnt(0)
	v_mfma_f32_16x16x32_bf16 v[16:19], v[32:35], v[28:31], v[16:19]
	ds_read_b64 v[32:33], v103 offset:36864
	ds_read_b64 v[34:35], v104 offset:36864
	v_fmac_f32_e32 v42, 0x3fb8aa3b, v6
	v_add_f32_e32 v7, v10, v11
	v_exp_f32_e32 v11, v42
	s_waitcnt lgkmcnt(0)
	v_mfma_f32_16x16x32_bf16 v[20:23], v[32:35], v[28:31], v[20:23]
	ds_read_b64 v[32:33], v105 offset:36864
	ds_read_b64 v[34:35], v106 offset:36864
	v_add_f32_e32 v6, v11, v7
	ds_bpermute_b32 v7, v75, v6
	s_waitcnt lgkmcnt(1)
	v_mfma_f32_16x16x32_bf16 v[24:27], v[32:35], v[28:31], v[24:27]
	ds_read_b64 v[32:33], v107 offset:36864
	ds_read_b64 v[34:35], v108 offset:36864
	s_waitcnt lgkmcnt(2)
	v_add_f32_e32 v6, v6, v7
	ds_bpermute_b32 v7, v76, v6
	v_sub_f32_e32 v4, v4, v5
	v_mul_f32_e32 v4, 0x3fb8aa3b, v4
	s_waitcnt lgkmcnt(1)
	v_mfma_f32_16x16x32_bf16 v[12:15], v[32:35], v[28:31], v[12:15]
	v_cvt_pk_bf16_f32 v8, v9, v8
	v_cvt_pk_bf16_f32 v9, v10, v11
	ds_read_b64 v[30:31], v116 offset:36864
	ds_read_b64 v[28:29], v115 offset:36864
	ds_read_b64 v[34:35], v114 offset:36864
	ds_read_b64 v[32:33], v113 offset:36864
	ds_read_b64 v[38:39], v112 offset:36864
	ds_read_b64 v[36:37], v111 offset:36864
	ds_read_b64 v[42:43], v110 offset:36864
	ds_read_b64 v[40:41], v109 offset:36864
	v_exp_f32_e32 v4, v4
	s_waitcnt lgkmcnt(8)
	v_add_f32_e32 v5, v6, v7
	v_mov_b32_e32 v10, v179
	v_mov_b32_e32 v11, v179
	v_add_f32_e32 v44, v4, v5
	v_or_b32_e32 v48, s0, v50
	s_waitcnt lgkmcnt(0)
	v_mfma_f32_16x16x32_bf16 v[4:7], v[40:43], v[8:11], v[16:19]
	v_readlane_b32 s0, v254, 50
	s_add_i32 s58, s58, s0
	s_cmpk_gt_i32 s58, 0xff
	v_mfma_f32_16x16x32_bf16 v[16:19], v[36:39], v[8:11], v[20:23]
	v_mfma_f32_16x16x32_bf16 v[20:23], v[32:35], v[8:11], v[24:27]
	v_mfma_f32_16x16x32_bf16 v[8:11], v[28:31], v[8:11], v[12:15]
	s_nop 2
	v_rcp_f32_e32 v12, v44
	v_lshlrev_b64 v[14:15], 7, v[48:49]
	v_pk_mul_f32 v[6:7], v[6:7], v[12:13] op_sel_hi:[1,0]
	v_pk_mul_f32 v[4:5], v[4:5], v[12:13] op_sel_hi:[1,0]
	s_nop 0
	v_pk_mul_f32 v[8:9], v[8:9], v[12:13] op_sel_hi:[1,0]
	v_cvt_pk_bf16_f32 v4, v4, v5
	v_cvt_pk_bf16_f32 v5, v6, v7
	v_lshl_add_u64 v[6:7], v[64:65], 0, v[14:15]
	v_pk_mul_f32 v[14:15], v[16:17], v[12:13] op_sel_hi:[1,0]
	global_store_dwordx2 v[6:7], v[4:5], off
	v_pk_mul_f32 v[4:5], v[18:19], v[12:13] op_sel_hi:[1,0]
	v_cvt_pk_bf16_f32 v14, v14, v15
	s_nop 0
	v_cvt_pk_bf16_f32 v15, v4, v5
	global_store_dwordx2 v[6:7], v[14:15], off offset:32
	v_pk_mul_f32 v[4:5], v[22:23], v[12:13] op_sel_hi:[1,0]
	v_pk_mul_f32 v[14:15], v[20:21], v[12:13] op_sel_hi:[1,0]
	s_nop 0
	v_cvt_pk_bf16_f32 v14, v14, v15
	v_cvt_pk_bf16_f32 v15, v4, v5
	global_store_dwordx2 v[6:7], v[14:15], off offset:64
	v_pk_mul_f32 v[4:5], v[10:11], v[12:13] op_sel_hi:[1,0]
	v_cvt_pk_bf16_f32 v8, v8, v9
	s_nop 0
	v_cvt_pk_bf16_f32 v9, v4, v5
	global_store_dwordx2 v[6:7], v[8:9], off offset:96
	s_barrier
	s_cbranch_scc1 .LBB0_434

; #define GAS __attribute__((address_space(1)))
; __device__ __forceinline__ size_t PJ(int row, int col) { return ((size_t)(col >> 6) * SEQ + row) * 64 + (col & 63); }
; __device__ __forceinline__ void conv_phase(const GAS bf16_t* proj, const GAS float* cw, const GAS float* cb_, GAS bf16_t* mix, int tid, int G, int bid) {
;     ...
;         for (int q = 0; q < 4; ++q) cbr[q] = *(const GAS u32x4*)(proj + PJ(t0 + q, C_CB + c8));
;         f32x4 w[3][2], bias[2];
; #pragma unroll
;         for (int d = 0; d < 3; ++d) { w[d][0] = *(const GAS f32x4*)(cw + d * 256 + c8); w[d][1] = *(const GAS f32x4*)(cw + d * 256 + c8 + 4); }
;         bias[0] = *(const GAS f32x4*)(cb_ + c8); bias[1] = *(const GAS f32x4*)(cb_ + c8 + 4);
;         f32x4 z[6][2];
; #pragma unroll
;         for (int r = 0; r < 6; ++r) { f32x4 a0, a1, b0, b1; unpk8(ccr[r], a0, a1); unpk8(cur[r], b0, b1); z[r][0] = a0 * b0; z[r][1] = a1 * b1; }
.LBB0_436:
	s_or_b64 exec, exec, s[8:9]
	v_add_u32_e32 v3, 0x2200000, v15
	v_and_b32_e32 v3, 0x2700000, v3
	v_lshlrev_b32_e32 v4, 1, v3
	v_mov_b32_e32 v5, v179
	v_lshl_add_u64 v[4:5], s[94:95], 0, v[4:5]
	v_ashrrev_i32_e32 v3, 31, v2
	v_ashrrev_i32_e32 v9, 31, v8
	v_lshl_add_u64 v[4:5], v[4:5], 0, v[178:179]
	v_lshlrev_b64 v[2:3], 7, v[2:3]
	v_lshlrev_b64 v[6:7], 7, v[8:9]
	v_lshl_add_u64 v[2:3], v[4:5], 0, v[2:3]
	v_lshl_add_u64 v[6:7], v[4:5], 0, v[6:7]
	v_ashrrev_i32_e32 v11, 31, v10
	v_ashrrev_i32_e32 v13, 31, v12
	v_mov_b32_e32 v94, v208
	v_mov_b32_e32 v95, v209
	v_mov_b32_e32 v96, v210
	v_mov_b32_e32 v97, v211
	v_mov_b32_e32 v62, v212
	v_mov_b32_e32 v63, v213
	v_mov_b32_e32 v64, v214
	v_mov_b32_e32 v65, v215
	v_lshlrev_b64 v[2:3], 7, v[10:11]
	v_lshlrev_b64 v[6:7], 7, v[12:13]
	v_lshl_add_u64 v[2:3], v[4:5], 0, v[2:3]
	v_lshl_add_u64 v[4:5], v[4:5], 0, v[6:7]
	v_lshlrev_b32_e32 v101, 2, v14
	v_mov_b32_e32 v42, v216
	v_mov_b32_e32 v43, v217
	v_mov_b32_e32 v44, v218
	v_mov_b32_e32 v45, v219
	v_mov_b32_e32 v18, v228
	v_mov_b32_e32 v19, v229
	v_mov_b32_e32 v20, v230
	v_mov_b32_e32 v21, v231
	s_nop 0
	global_load_dwordx4 v[2:5], v101, s[2:3] offset:16
	global_load_dwordx4 v[22:25], v101, s[2:3]
	global_load_dwordx4 v[6:9], v101, s[2:3] offset:1040
	global_load_dwordx4 v[26:29], v101, s[2:3] offset:1024
	global_load_dwordx4 v[10:13], v101, s[2:3] offset:2064
	global_load_dwordx4 v[30:33], v101, s[2:3] offset:2048
	global_load_dwordx4 v[14:17], v101, s[4:5] offset:16
	global_load_dwordx4 v[34:37], v101, s[4:5]
	s_waitcnt vmcnt(13)
	v_lshlrev_b32_e32 v102, 16, v54
	v_and_b32_e32 v103, 0xffff0000, v54
	v_lshlrev_b32_e32 v54, 16, v55
	v_and_b32_e32 v55, 0xffff0000, v55
	v_lshlrev_b32_e32 v104, 16, v56
	v_and_b32_e32 v105, 0xffff0000, v56
	v_lshlrev_b32_e32 v56, 16, v57
	v_and_b32_e32 v57, 0xffff0000, v57
	s_waitcnt vmcnt(12)
	v_lshlrev_b32_e32 v106, 16, v50
	v_and_b32_e32 v107, 0xffff0000, v50
	v_lshlrev_b32_e32 v50, 16, v51
	v_and_b32_e32 v51, 0xffff0000, v51
	v_lshlrev_b32_e32 v108, 16, v52
	v_and_b32_e32 v109, 0xffff0000, v52
	v_lshlrev_b32_e32 v52, 16, v53
	v_and_b32_e32 v53, 0xffff0000, v53
	v_pk_mul_f32 v[110:111], v[50:51], v[54:55]
	v_pk_mul_f32 v[102:103], v[106:107], v[102:103]
	v_pk_mul_f32 v[106:107], v[52:53], v[56:57]
	v_lshlrev_b32_e32 v50, 16, v66
	v_and_b32_e32 v51, 0xffff0000, v66
	v_lshlrev_b32_e32 v52, 16, v67
	v_and_b32_e32 v53, 0xffff0000, v67
	v_lshlrev_b32_e32 v54, 16, v68
	v_and_b32_e32 v55, 0xffff0000, v68
	v_lshlrev_b32_e32 v56, 16, v69
	v_and_b32_e32 v57, 0xffff0000, v69
	v_lshlrev_b32_e32 v66, 16, v38
	v_and_b32_e32 v67, 0xffff0000, v38
	v_lshlrev_b32_e32 v38, 16, v39
	v_and_b32_e32 v39, 0xffff0000, v39
	v_lshlrev_b32_e32 v68, 16, v40
	v_and_b32_e32 v69, 0xffff0000, v40
	v_lshlrev_b32_e32 v40, 16, v41
	v_and_b32_e32 v41, 0xffff0000, v41
	v_pk_mul_f32 v[104:105], v[108:109], v[104:105]
	v_pk_mul_f32 v[66:67], v[66:67], v[50:51]
	v_pk_mul_f32 v[108:109], v[38:39], v[52:53]
	v_pk_mul_f32 v[112:113], v[40:41], v[56:57]
	v_lshlrev_b32_e32 v38, 16, v74
	v_and_b32_e32 v39, 0xffff0000, v74
	v_lshlrev_b32_e32 v40, 16, v75
	v_and_b32_e32 v41, 0xffff0000, v75
	v_lshlrev_b32_e32 v50, 16, v77
	v_and_b32_e32 v51, 0xffff0000, v77
	v_lshlrev_b32_e32 v56, 16, v70
	v_and_b32_e32 v57, 0xffff0000, v70
	v_lshlrev_b32_e32 v52, 16, v71
	v_and_b32_e32 v53, 0xffff0000, v71
	v_lshlrev_b32_e32 v70, 16, v72
	v_and_b32_e32 v71, 0xffff0000, v72
	v_lshlrev_b32_e32 v72, 16, v73
	v_and_b32_e32 v73, 0xffff0000, v73
	v_pk_mul_f32 v[68:69], v[68:69], v[54:55]
	v_lshlrev_b32_e32 v54, 16, v76
	v_and_b32_e32 v55, 0xffff0000, v76
	v_pk_mul_f32 v[52:53], v[52:53], v[40:41]
	v_pk_mul_f32 v[56:57], v[56:57], v[38:39]
	v_pk_mul_f32 v[50:51], v[72:73], v[50:51]
	v_lshlrev_b32_e32 v38, 16, v78
	v_and_b32_e32 v39, 0xffff0000, v78
	v_lshlrev_b32_e32 v40, 16, v79
	v_and_b32_e32 v41, 0xffff0000, v79
	v_lshlrev_b32_e32 v72, 16, v81
	v_and_b32_e32 v73, 0xffff0000, v81
	v_lshlrev_b32_e32 v74, 16, v46
	v_and_b32_e32 v75, 0xffff0000, v46
	v_lshlrev_b32_e32 v78, 16, v49
	v_and_b32_e32 v79, 0xffff0000, v49
	v_pk_mul_f32 v[54:55], v[70:71], v[54:55]
	v_lshlrev_b32_e32 v70, 16, v80
	v_and_b32_e32 v71, 0xffff0000, v80
	v_lshlrev_b32_e32 v46, 16, v47
	v_and_b32_e32 v47, 0xffff0000, v47
	v_lshlrev_b32_e32 v76, 16, v48
	v_and_b32_e32 v77, 0xffff0000, v48
	v_pk_mul_f32 v[48:49], v[74:75], v[38:39]
	v_pk_mul_f32 v[38:39], v[78:79], v[72:73]
	v_lshlrev_b32_e32 v72, 16, v87
	v_and_b32_e32 v73, 0xffff0000, v87
	v_lshlrev_b32_e32 v80, 16, v83
	v_and_b32_e32 v81, 0xffff0000, v83
	v_pk_mul_f32 v[40:41], v[46:47], v[40:41]
	v_pk_mul_f32 v[46:47], v[76:77], v[70:71]
	v_lshlrev_b32_e32 v70, 16, v86
	v_and_b32_e32 v71, 0xffff0000, v86
	v_pk_mul_f32 v[72:73], v[80:81], v[72:73]
	v_lshlrev_b32_e32 v80, 16, v91
	v_and_b32_e32 v81, 0xffff0000, v91
	v_lshlrev_b32_e32 v86, 16, v58
	v_and_b32_e32 v87, 0xffff0000, v58
	v_lshlrev_b32_e32 v58, 16, v59
	v_and_b32_e32 v59, 0xffff0000, v59
	v_lshlrev_b32_e32 v78, 16, v82
	v_and_b32_e32 v79, 0xffff0000, v82
	v_pk_mul_f32 v[80:81], v[58:59], v[80:81]
	v_ashrrev_i32_e32 v58, 11, v100
	v_lshlrev_b32_e32 v76, 16, v89
	v_and_b32_e32 v77, 0xffff0000, v89
	v_lshlrev_b32_e32 v82, 16, v84
	v_and_b32_e32 v83, 0xffff0000, v84
	v_lshlrev_b32_e32 v84, 16, v85
	v_and_b32_e32 v85, 0xffff0000, v85
	v_pk_mul_f32 v[70:71], v[78:79], v[70:71]
	v_lshlrev_b32_e32 v78, 16, v90
	v_and_b32_e32 v79, 0xffff0000, v90
	v_ashrrev_i32_e32 v59, 31, v58
	v_lshlrev_b32_e32 v74, 16, v88
	v_and_b32_e32 v75, 0xffff0000, v88
	v_pk_mul_f32 v[76:77], v[84:85], v[76:77]
	v_lshlrev_b32_e32 v84, 16, v93
	v_and_b32_e32 v85, 0xffff0000, v93
	v_lshlrev_b32_e32 v88, 16, v60
	v_and_b32_e32 v89, 0xffff0000, v60
	v_lshlrev_b32_e32 v60, 16, v61
	v_and_b32_e32 v61, 0xffff0000, v61
	v_pk_mul_f32 v[78:79], v[86:87], v[78:79]
	v_lshlrev_b64 v[86:87], 12, v[58:59]
	v_and_b32_e32 v58, 0x300, v101
	v_and_b32_e32 v59, 0xfc, v99
	v_pk_mul_f32 v[84:85], v[60:61], v[84:85]
	v_or3_b32 v99, v58, v86, v59
	s_waitcnt vmcnt(11)
; __device__ __forceinline__ unsigned cvt_pk_bf16(float lo, float hi) { unsigned r; asm volatile("v_cvt_pk_bf16_f32 %0, %1, %2" : "=v"(r) : "v"(lo), "v"(hi)); return r; }
; #define GAS __attribute__((address_space(1)))
; __device__ __forceinline__ size_t TX(int row, int col) { return ((((size_t)(row >> 8) * 16 + (col >> 6)) * 256 + (row & 255)) << 6) + (col & 63); }
; __device__ __forceinline__ void conv_phase(const GAS bf16_t* proj, const GAS float* cw, const GAS float* cb_, GAS bf16_t* mix, int tid, int G, int bid) {
;     ...
; #pragma unroll
;         for (int q = 0; q < 4; ++q) {
;             f32x4 g0, g1; unpk8(cbr[q], g0, g1);
;             const f32x4 y0 = g0 * (bias[0] + z[q][0] * w[0][0] + z[q + 1][0] * w[1][0] + z[q + 2][0] * w[2][0]);
;             const f32x4 y1 = g1 * (bias[1] + z[q][1] * w[0][1] + z[q + 1][1] * w[1][1] + z[q + 2][1] * w[2][1]);
;             u32x4 o; o.x = cvt_pk_bf16(y0[0], y0[1]); o.y = cvt_pk_bf16(y0[2], y0[3]); o.z = cvt_pk_bf16(y1[0], y1[1]); o.w = cvt_pk_bf16(y1[2], y1[3]);
;             *(GAS u32x4*)(mix + TX(t0 + q, MIX_CONV + c8)) = o;
;         }
;     }
	v_lshlrev_b32_e32 v58, 16, v94
	v_and_b32_e32 v59, 0xffff0000, v94
	v_lshlrev_b32_e32 v60, 16, v95
	v_and_b32_e32 v61, 0xffff0000, v95
	s_waitcnt vmcnt(0)
	v_pk_fma_f32 v[94:95], v[102:103], v[22:23], v[34:35]
	v_pk_mul_f32 v[74:75], v[82:83], v[74:75]
	v_pk_fma_f32 v[94:95], v[66:67], v[26:27], v[94:95]
	v_lshlrev_b32_e32 v82, 16, v92
	v_pk_fma_f32 v[94:95], v[56:57], v[30:31], v[94:95]
	v_and_b32_e32 v83, 0xffff0000, v92
	v_lshlrev_b32_e32 v90, 16, v96
	v_and_b32_e32 v91, 0xffff0000, v96
	v_lshlrev_b32_e32 v92, 16, v97
	v_and_b32_e32 v93, 0xffff0000, v97
	v_pk_fma_f32 v[96:97], v[110:111], v[24:25], v[36:37]
	v_pk_mul_f32 v[58:59], v[94:95], v[58:59]
	v_pk_fma_f32 v[94:95], v[104:105], v[2:3], v[14:15]
	v_pk_fma_f32 v[96:97], v[108:109], v[28:29], v[96:97]
	v_pk_fma_f32 v[94:95], v[68:69], v[6:7], v[94:95]
	v_readlane_b32 s8, v254, 57
	v_pk_fma_f32 v[96:97], v[52:53], v[32:33], v[96:97]
	v_pk_fma_f32 v[94:95], v[54:55], v[10:11], v[94:95]
	v_readlane_b32 s9, v254, 58
	v_pk_mul_f32 v[60:61], v[96:97], v[60:61]
	v_pk_fma_f32 v[96:97], v[106:107], v[4:5], v[16:17]
	v_pk_mul_f32 v[90:91], v[94:95], v[90:91]
	v_or_b32_e32 v86, 0xc00, v99
	v_pk_mul_f32 v[82:83], v[88:89], v[82:83]
	v_lshl_add_u64 v[88:89], s[8:9], 0, v[178:179]
	v_pk_fma_f32 v[96:97], v[112:113], v[8:9], v[96:97]
	v_cvt_pk_bf16_f32 v58, v58, v59
	v_cvt_pk_bf16_f32 v59, v60, v61
	v_cvt_pk_bf16_f32 v60, v90, v91
	v_lshlrev_b64 v[90:91], 7, v[86:87]
	v_pk_fma_f32 v[66:67], v[66:67], v[22:23], v[34:35]
	v_pk_fma_f32 v[96:97], v[50:51], v[12:13], v[96:97]
	v_lshl_add_u64 v[90:91], v[88:89], 0, v[90:91]
	v_pk_fma_f32 v[66:67], v[56:57], v[26:27], v[66:67]
	v_pk_mul_f32 v[92:93], v[96:97], v[92:93]
	v_pk_fma_f32 v[66:67], v[48:49], v[30:31], v[66:67]
	v_cvt_pk_bf16_f32 v61, v92, v93
	global_store_dwordx4 v[90:91], v[58:61], off
	v_pk_fma_f32 v[90:91], v[108:109], v[24:25], v[36:37]
	v_or_b32_e32 v86, 0xc01, v99
	v_lshlrev_b32_e32 v58, 16, v62
	v_and_b32_e32 v59, 0xffff0000, v62
	v_pk_mul_f32 v[58:59], v[66:67], v[58:59]
	v_pk_fma_f32 v[66:67], v[68:69], v[2:3], v[14:15]
	v_pk_fma_f32 v[90:91], v[52:53], v[28:29], v[90:91]
	v_pk_fma_f32 v[66:67], v[54:55], v[6:7], v[66:67]
	v_lshlrev_b32_e32 v60, 16, v63
	v_and_b32_e32 v61, 0xffff0000, v63
	v_lshlrev_b32_e32 v62, 16, v64
	v_and_b32_e32 v63, 0xffff0000, v64
	v_pk_fma_f32 v[90:91], v[40:41], v[32:33], v[90:91]
	v_pk_fma_f32 v[68:69], v[112:113], v[4:5], v[16:17]
	v_pk_fma_f32 v[66:67], v[46:47], v[10:11], v[66:67]
	v_pk_mul_f32 v[60:61], v[90:91], v[60:61]
	v_pk_fma_f32 v[68:69], v[50:51], v[8:9], v[68:69]
	v_pk_mul_f32 v[62:63], v[66:67], v[62:63]
	v_lshlrev_b32_e32 v64, 16, v65
	v_and_b32_e32 v65, 0xffff0000, v65
	v_pk_fma_f32 v[68:69], v[38:39], v[12:13], v[68:69]
	v_cvt_pk_bf16_f32 v58, v58, v59
	v_cvt_pk_bf16_f32 v59, v60, v61
	v_cvt_pk_bf16_f32 v60, v62, v63
	v_lshlrev_b64 v[62:63], 7, v[86:87]
	v_pk_fma_f32 v[56:57], v[56:57], v[22:23], v[34:35]
	v_pk_fma_f32 v[52:53], v[52:53], v[24:25], v[36:37]
	v_pk_fma_f32 v[54:55], v[54:55], v[2:3], v[14:15]
	v_pk_fma_f32 v[50:51], v[50:51], v[4:5], v[16:17]
	v_pk_mul_f32 v[64:65], v[68:69], v[64:65]
	v_lshl_add_u64 v[62:63], v[88:89], 0, v[62:63]
	v_cvt_pk_bf16_f32 v61, v64, v65
	v_pk_fma_f32 v[52:53], v[40:41], v[28:29], v[52:53]
	v_pk_fma_f32 v[56:57], v[48:49], v[26:27], v[56:57]
	v_pk_fma_f32 v[50:51], v[38:39], v[8:9], v[50:51]
	v_pk_fma_f32 v[54:55], v[46:47], v[6:7], v[54:55]
	global_store_dwordx4 v[62:63], v[58:61], off
	v_pk_fma_f32 v[56:57], v[70:71], v[30:31], v[56:57]
	v_pk_fma_f32 v[52:53], v[72:73], v[32:33], v[52:53]
	v_lshlrev_b32_e32 v58, 16, v42
	v_and_b32_e32 v59, 0xffff0000, v42
	v_lshlrev_b32_e32 v42, 16, v43
	v_and_b32_e32 v43, 0xffff0000, v43
	v_lshlrev_b32_e32 v60, 16, v44
	v_and_b32_e32 v61, 0xffff0000, v44
	v_lshlrev_b32_e32 v44, 16, v45
	v_and_b32_e32 v45, 0xffff0000, v45
	v_pk_fma_f32 v[54:55], v[74:75], v[10:11], v[54:55]
	v_pk_fma_f32 v[50:51], v[76:77], v[12:13], v[50:51]
	v_pk_mul_f32 v[52:53], v[52:53], v[42:43]
	v_pk_mul_f32 v[42:43], v[56:57], v[58:59]
	v_pk_mul_f32 v[50:51], v[50:51], v[44:45]
	v_pk_mul_f32 v[44:45], v[54:55], v[60:61]
	v_or_b32_e32 v86, 0xc02, v99
	v_cvt_pk_bf16_f32 v42, v42, v43
	v_cvt_pk_bf16_f32 v43, v52, v53
	v_cvt_pk_bf16_f32 v44, v44, v45
	v_cvt_pk_bf16_f32 v45, v50, v51
	v_lshlrev_b64 v[50:51], 7, v[86:87]
	v_pk_fma_f32 v[2:3], v[46:47], v[2:3], v[14:15]
	v_pk_fma_f32 v[4:5], v[38:39], v[4:5], v[16:17]
	v_lshl_add_u64 v[50:51], v[88:89], 0, v[50:51]
	v_pk_fma_f32 v[22:23], v[48:49], v[22:23], v[34:35]
	v_pk_fma_f32 v[24:25], v[40:41], v[24:25], v[36:37]
	v_pk_fma_f32 v[4:5], v[76:77], v[8:9], v[4:5]
	v_pk_fma_f32 v[2:3], v[74:75], v[6:7], v[2:3]
	global_store_dwordx4 v[50:51], v[42:45], off
	v_pk_fma_f32 v[24:25], v[72:73], v[28:29], v[24:25]
	v_pk_fma_f32 v[22:23], v[70:71], v[26:27], v[22:23]
	v_lshlrev_b32_e32 v44, 16, v20
	v_and_b32_e32 v45, 0xffff0000, v20
	v_lshlrev_b32_e32 v20, 16, v21
	v_and_b32_e32 v21, 0xffff0000, v21
	v_pk_fma_f32 v[2:3], v[82:83], v[10:11], v[2:3]
	v_pk_fma_f32 v[4:5], v[84:85], v[12:13], v[4:5]
	v_lshlrev_b32_e32 v42, 16, v18
	v_and_b32_e32 v43, 0xffff0000, v18
	v_lshlrev_b32_e32 v18, 16, v19
	v_and_b32_e32 v19, 0xffff0000, v19
	v_pk_fma_f32 v[22:23], v[78:79], v[30:31], v[22:23]
	v_pk_fma_f32 v[24:25], v[80:81], v[32:33], v[24:25]
	v_pk_mul_f32 v[6:7], v[4:5], v[20:21]
	v_pk_mul_f32 v[4:5], v[2:3], v[44:45]
	v_or_b32_e32 v86, 0xc03, v99
	v_add_u32_e32 v1, s10, v1
	v_pk_mul_f32 v[18:19], v[24:25], v[18:19]
	v_pk_mul_f32 v[22:23], v[22:23], v[42:43]
	v_cmp_lt_i32_e32 vcc, s11, v1
	v_cvt_pk_bf16_f32 v2, v22, v23
	v_cvt_pk_bf16_f32 v3, v18, v19
	v_cvt_pk_bf16_f32 v4, v4, v5
	v_cvt_pk_bf16_f32 v5, v6, v7
	v_lshlrev_b64 v[6:7], 7, v[86:87]
	v_lshl_add_u64 v[6:7], v[88:89], 0, v[6:7]
	s_or_b64 s[6:7], vcc, s[6:7]
	global_store_dwordx4 v[6:7], v[2:5], off
	s_andn2_b64 exec, exec, s[6:7]
	s_cbranch_execz .LBB0_449
; #define GAS __attribute__((address_space(1)))
; __device__ __forceinline__ size_t PJ(int row, int col) { return ((size_t)(col >> 6) * SEQ + row) * 64 + (col & 63); }
; __device__ __forceinline__ void conv_phase(const GAS bf16_t* proj, const GAS float* cw, const GAS float* cb_, GAS bf16_t* mix, int tid, int G, int bid) {
;     ...
;         const int it = (G == 256) ? (((512 * (bid & 7) + 16 * (bid >> 3)) << 5) + tid) : it0;
;         const int t0 = (it >> 5) * 4, c8 = (it & 31) * 8;
;         u32x4 ccr[6], cur[6], cbr[4];
; #pragma unroll
;         for (int r = 0; r < 6; ++r) { const int tt = t0 - 2 + r;
;             ccr[r] = (u32x4){0u, 0u, 0u, 0u}; cur[r] = (u32x4){0u, 0u, 0u, 0u};
;             if (tt >= 0) { ccr[r] = *(const GAS u32x4*)(proj + PJ(tt, C_CC + c8)); cur[r] = *(const GAS u32x4*)(proj + PJ(tt, C_CU + c8)); } }
.LBB0_437:
	s_waitcnt vmcnt(4)
	v_cndmask_b32_e64 v100, v1, v98, s[62:63]
	s_waitcnt lgkmcnt(0)
	v_lshlrev_b32_e32 v3, 3, v100
	v_and_b32_e32 v14, 0xf8, v3
	v_lshlrev_b32_e32 v15, 14, v14
	v_add_u32_e32 v4, 0x2600000, v15
	v_and_b32_e32 v4, 0x2f00000, v4
	v_and_b32_e32 v3, 56, v3
	v_lshlrev_b32_e32 v178, 1, v4
	v_lshl_add_u64 v[4:5], s[94:95], 0, v[178:179]
	v_lshlrev_b32_e32 v178, 1, v3
	v_add_u32_e32 v3, 0x2a00000, v15
	v_and_b32_e32 v3, 0x2f00000, v3
	v_lshlrev_b32_e32 v6, 1, v3
	v_mov_b32_e32 v7, v179
	v_ashrrev_i32_e32 v99, 3, v100
	v_lshl_add_u64 v[6:7], s[94:95], 0, v[6:7]
	v_and_b32_e32 v2, -4, v99
	v_lshl_add_u64 v[4:5], v[4:5], 0, v[178:179]
	v_lshl_add_u64 v[6:7], v[6:7], 0, v[178:179]
	v_cmp_lt_i32_e32 vcc, 3, v99
	v_mov_b32_e32 v38, 0
	v_mov_b32_e32 v50, 0
	v_mov_b32_e32 v51, 0
	v_mov_b32_e32 v52, 0
	v_mov_b32_e32 v53, 0
	v_mov_b32_e32 v54, 0
	v_mov_b32_e32 v55, 0
	v_mov_b32_e32 v56, 0
	v_mov_b32_e32 v57, 0
	s_and_saveexec_b64 s[8:9], vcc
	s_cbranch_execz .LBB0_439
	v_add_u32_e32 v8, -2, v2
	v_mov_b32_e32 v9, v179
	v_lshlrev_b64 v[8:9], 7, v[8:9]
	v_lshl_add_u64 v[10:11], v[6:7], 0, v[8:9]
	v_lshl_add_u64 v[8:9], v[4:5], 0, v[8:9]
	v_mov_b32_e32 v54, v154
	v_mov_b32_e32 v55, v155
	v_mov_b32_e32 v56, v156
	v_mov_b32_e32 v57, v157
	v_mov_b32_e32 v50, v180
	v_mov_b32_e32 v51, v181
	v_mov_b32_e32 v52, v182
	v_mov_b32_e32 v53, v183
.LBB0_439:
	s_or_b64 exec, exec, s[8:9]
	v_mov_b32_e32 v39, 0
	v_mov_b32_e32 v40, 0
	v_mov_b32_e32 v41, 0
	v_mov_b32_e32 v66, 0
	v_mov_b32_e32 v67, 0
	v_mov_b32_e32 v68, 0
	v_mov_b32_e32 v69, 0
	s_and_saveexec_b64 s[8:9], vcc
	s_cbranch_execz .LBB0_441
	v_add_u32_e32 v8, -1, v2
	v_mov_b32_e32 v9, v179
	v_lshlrev_b64 v[8:9], 7, v[8:9]
	v_lshl_add_u64 v[10:11], v[6:7], 0, v[8:9]
	v_lshl_add_u64 v[8:9], v[4:5], 0, v[8:9]
	v_mov_b32_e32 v66, v158
	v_mov_b32_e32 v67, v159
	v_mov_b32_e32 v68, v160
	v_mov_b32_e32 v69, v161
	v_mov_b32_e32 v38, v186
	v_mov_b32_e32 v39, v187
	v_mov_b32_e32 v40, v188
	v_mov_b32_e32 v41, v189
.LBB0_441:
	s_or_b64 exec, exec, s[8:9]
	v_cmp_lt_i32_e32 vcc, -1, v99
	v_mov_b32_e32 v46, 0
	v_mov_b32_e32 v70, 0
	v_mov_b32_e32 v71, 0
	v_mov_b32_e32 v72, 0
	v_mov_b32_e32 v73, 0
	v_mov_b32_e32 v74, 0
	v_mov_b32_e32 v75, 0
	v_mov_b32_e32 v76, 0
	v_mov_b32_e32 v77, 0
	s_and_saveexec_b64 s[8:9], vcc
	s_cbranch_execz .LBB0_443
	v_mov_b32_e32 v3, v179
	v_lshlrev_b64 v[8:9], 7, v[2:3]
	v_lshl_add_u64 v[10:11], v[6:7], 0, v[8:9]
	v_lshl_add_u64 v[8:9], v[4:5], 0, v[8:9]
	v_mov_b32_e32 v74, v162
	v_mov_b32_e32 v75, v163
	v_mov_b32_e32 v76, v164
	v_mov_b32_e32 v77, v165
	v_mov_b32_e32 v70, v190
	v_mov_b32_e32 v71, v191
	v_mov_b32_e32 v72, v192
	v_mov_b32_e32 v73, v193
.LBB0_443:
	s_or_b64 exec, exec, s[8:9]
	v_or_b32_e32 v8, 1, v2
	v_mov_b32_e32 v47, 0
	v_mov_b32_e32 v48, 0
	v_mov_b32_e32 v49, 0
	v_mov_b32_e32 v78, 0
	v_mov_b32_e32 v79, 0
	v_mov_b32_e32 v80, 0
	v_mov_b32_e32 v81, 0
	s_and_saveexec_b64 s[8:9], vcc
	s_cbranch_execz .LBB0_445
	v_mov_b32_e32 v9, v179
	v_lshlrev_b64 v[10:11], 7, v[8:9]
	v_lshl_add_u64 v[12:13], v[6:7], 0, v[10:11]
	v_lshl_add_u64 v[10:11], v[4:5], 0, v[10:11]
	v_mov_b32_e32 v78, v166
	v_mov_b32_e32 v79, v167
	v_mov_b32_e32 v80, v168
	v_mov_b32_e32 v81, v169
	v_mov_b32_e32 v46, v196
	v_mov_b32_e32 v47, v197
	v_mov_b32_e32 v48, v198
	v_mov_b32_e32 v49, v199
.LBB0_445:
	s_or_b64 exec, exec, s[8:9]
	v_mov_b32_e32 v58, 0
	v_or_b32_e32 v10, 2, v2
	s_nop 0
	v_mov_b32_e32 v82, 0
	v_mov_b32_e32 v83, 0
	v_mov_b32_e32 v84, 0
	v_mov_b32_e32 v85, 0
	v_mov_b32_e32 v86, 0
	v_mov_b32_e32 v87, 0
	v_mov_b32_e32 v88, 0
	v_mov_b32_e32 v89, 0
	s_and_saveexec_b64 s[8:9], vcc
	s_cbranch_execz .LBB0_447
	v_mov_b32_e32 v11, v179
	v_lshlrev_b64 v[12:13], 7, v[10:11]
	v_lshl_add_u64 v[16:17], v[6:7], 0, v[12:13]
	v_lshl_add_u64 v[12:13], v[4:5], 0, v[12:13]
	v_mov_b32_e32 v86, v170
	v_mov_b32_e32 v87, v171
	v_mov_b32_e32 v88, v172
	v_mov_b32_e32 v89, v173
	v_mov_b32_e32 v82, v200
	v_mov_b32_e32 v83, v201
	v_mov_b32_e32 v84, v202
	v_mov_b32_e32 v85, v203
.LBB0_447:
	s_or_b64 exec, exec, s[8:9]
	v_or_b32_e32 v12, 3, v99
	v_mov_b32_e32 v59, 0
	v_mov_b32_e32 v60, 0
	v_mov_b32_e32 v61, 0
	v_mov_b32_e32 v90, 0
	v_mov_b32_e32 v91, 0
	v_mov_b32_e32 v92, 0
	v_mov_b32_e32 v93, 0
	s_and_saveexec_b64 s[8:9], vcc
	s_cbranch_execz .LBB0_436
	v_mov_b32_e32 v13, v179
	v_lshlrev_b64 v[16:17], 7, v[12:13]
	v_lshl_add_u64 v[4:5], v[4:5], 0, v[16:17]
	v_lshl_add_u64 v[6:7], v[6:7], 0, v[16:17]
	v_mov_b32_e32 v90, v174
	v_mov_b32_e32 v91, v175
	v_mov_b32_e32 v92, v176
	v_mov_b32_e32 v93, v177
	v_mov_b32_e32 v58, v204
	v_mov_b32_e32 v59, v205
	v_mov_b32_e32 v60, v206
	v_mov_b32_e32 v61, v207
	s_branch .LBB0_436

; __global__ void __launch_bounds__(512, 2) fwd(Args a) {
	.amdhsa_kernel _Z3fwd4Args
		.amdhsa_group_segment_fixed_size 0
		.amdhsa_private_segment_fixed_size 0
		.amdhsa_kernarg_size 408
		.amdhsa_user_sgpr_count 2
		.amdhsa_user_sgpr_dispatch_ptr 0
		.amdhsa_user_sgpr_queue_ptr 0
		.amdhsa_user_sgpr_kernarg_segment_ptr 1
		.amdhsa_user_sgpr_dispatch_id 0
		.amdhsa_user_sgpr_kernarg_preload_length 0
		.amdhsa_user_sgpr_kernarg_preload_offset 0
		.amdhsa_user_sgpr_private_segment_size 0
		.amdhsa_uses_dynamic_stack 0
		.amdhsa_enable_private_segment 0
		.amdhsa_system_sgpr_workgroup_id_x 1
		.amdhsa_system_sgpr_workgroup_id_y 0
		.amdhsa_system_sgpr_workgroup_id_z 0
		.amdhsa_system_sgpr_workgroup_info 0
		.amdhsa_system_vgpr_workitem_id 2
		.amdhsa_next_free_vgpr 256
		.amdhsa_next_free_sgpr 102
		.amdhsa_accum_offset 256
		.amdhsa_reserve_vcc 1
		.amdhsa_float_round_mode_32 0
		.amdhsa_float_round_mode_16_64 0
		.amdhsa_float_denorm_mode_32 3
		.amdhsa_float_denorm_mode_16_64 3
		.amdhsa_dx10_clamp 1
		.amdhsa_ieee_mode 1
		.amdhsa_fp16_overflow 0
		.amdhsa_tg_split 0
		.amdhsa_exception_fp_ieee_invalid_op 0
		.amdhsa_exception_fp_denorm_src 0
		.amdhsa_exception_fp_ieee_div_zero 0
		.amdhsa_exception_fp_ieee_overflow 0
		.amdhsa_exception_fp_ieee_underflow 0
		.amdhsa_exception_fp_ieee_inexact 0
		.amdhsa_exception_int_div_zero 0
	.end_amdhsa_kernel

; __global__ void __launch_bounds__(512, 2) fwd(Args a) {
amdhsa.kernels:
  - .agpr_count:     0
    .args:
      - .offset:         0
        .size:           152
        .value_kind:     by_value
      - .offset:         152
        .size:           4
        .value_kind:     hidden_block_count_x
      - .offset:         156
        .size:           4
        .value_kind:     hidden_block_count_y
      - .offset:         160
        .size:           4
        .value_kind:     hidden_block_count_z
      - .offset:         164
        .size:           2
        .value_kind:     hidden_group_size_x
      - .offset:         166
        .size:           2
        .value_kind:     hidden_group_size_y
      - .offset:         168
        .size:           2
        .value_kind:     hidden_group_size_z
      - .offset:         170
        .size:           2
        .value_kind:     hidden_remainder_x
      - .offset:         172
        .size:           2
        .value_kind:     hidden_remainder_y
      - .offset:         174
        .size:           2
        .value_kind:     hidden_remainder_z
      - .offset:         192
        .size:           8
        .value_kind:     hidden_global_offset_x
      - .offset:         200
        .size:           8
        .value_kind:     hidden_global_offset_y
      - .offset:         208
        .size:           8
        .value_kind:     hidden_global_offset_z
      - .offset:         216
        .size:           2
        .value_kind:     hidden_grid_dims
      - .offset:         240
        .size:           8
        .value_kind:     hidden_multigrid_sync_arg
      - .offset:         272
        .size:           4
        .value_kind:     hidden_dynamic_lds_size
    .group_segment_fixed_size: 0
    .kernarg_segment_align: 8
    .kernarg_segment_size: 408
    .language:       OpenCL C
    .language_version:
      - 2
      - 0
    .max_flat_workgroup_size: 512
    .name:           _Z3fwd4Args
    .private_segment_fixed_size: 0
    .sgpr_count:     108
    .sgpr_spill_count: 130
    .symbol:         _Z3fwd4Args.kd
    .uniform_work_group_size: 1
    .uses_dynamic_stack: false
    .vgpr_count:     256
    .vgpr_spill_count: 0
    .wavefront_size: 64
